# v38: v34 + loop-invariant groupnorm weight/bias loads hoisted out of the mix_rwkv loop
# baseline (speedup 1.0000x reference)
.LBB0_1393:
	s_or_b64 exec, exec, s[4:5]
	v_mov_b32_e32 v1, v166
	s_barrier
	s_lshl_b32 s4, s37, 2
	v_ashrrev_i32_e32 v0, 6, v1
	v_add_u32_e32 v4, s36, v0
	s_mov_b32 s0, 0x8000
	v_cmp_gt_i32_e32 vcc, s0, v4
	s_mov_b64 s[6:7], exec
	v_readlane_b32 s8, v254, 13
	v_readlane_b32 s14, v254, 19
	v_readlane_b32 s15, v254, 20
	v_readlane_b32 s16, v254, 21
	v_readlane_b32 s17, v254, 22
	v_readlane_b32 s18, v254, 23
	v_readlane_b32 s19, v254, 24
	v_readlane_b32 s20, v254, 25
	v_readlane_b32 s21, v254, 26
	v_readlane_b32 s22, v254, 27
	v_readlane_b32 s23, v254, 28
	s_mov_b64 s[14:15], s[18:19]
	v_readlane_b32 s16, v255, 45
	s_and_b64 s[0:1], s[6:7], vcc
	v_readlane_b32 s17, v255, 46
	v_readlane_b32 s18, v255, 47
	v_readlane_b32 s19, v255, 48
	v_readlane_b32 s20, v255, 49
	v_readlane_b32 s21, v255, 50
	v_readlane_b32 s9, v254, 14
	v_readlane_b32 s10, v254, 15
	v_readlane_b32 s11, v254, 16
	v_readlane_b32 s12, v254, 17
	v_readlane_b32 s13, v254, 18
	v_readlane_b32 s22, v255, 51
	v_readlane_b32 s23, v255, 52
	v_readlane_b32 s24, v255, 53
	v_readlane_b32 s25, v255, 54
	v_readlane_b32 s26, v255, 55
	v_readlane_b32 s27, v255, 56
	v_readlane_b32 s28, v255, 57
	v_readlane_b32 s29, v255, 58
	v_readlane_b32 s30, v255, 59
	v_readlane_b32 s31, v255, 60
	s_mov_b64 exec, s[0:1]
	s_cbranch_execz .LBB0_1396
	v_bfe_u32 v5, v1, 4, 2
	v_lshlrev_b32_e32 v1, 2, v1
	v_lshlrev_b32_e32 v0, 2, v0
	v_readlane_b32 s0, v255, 12
	v_and_b32_e32 v6, 60, v1
	s_mov_b64 s[8:9], 0
	v_lshl_add_u32 v7, s0, 4, v0
	s_lshl_b32 s0, s37, 4
	v_mov_b32_e32 v8, 0x3a27c5ac
	s_mov_b32 s1, 0x800000
	s_movk_i32 s2, 0x880
	v_mov_b64_e32 v[0:1], s[88:89]
	v_mov_b32_e32 v3, 0
	s_movk_i32 s3, 0x7fff
	v_and_or_b32 v46, v7, 4, v5
	v_lshl_or_b32 v46, v46, 6, v6
	v_lshlrev_b32_e32 v46, 2, v46
	global_load_dwordx4 v[14:17], v46, s[18:19]
	global_load_dwordx4 v[18:21], v46, s[20:21]
.LBB0_1395:
	s_waitcnt vmcnt(1)
	v_ashrrev_i32_e32 v26, 1, v4
	v_and_or_b32 v2, v7, 4, v5
	v_ashrrev_i32_e32 v27, 31, v26
	v_lshl_or_b32 v2, v2, 6, v6
	v_lshlrev_b64 v[22:23], 9, v[26:27]
	v_or_b32_e32 v22, v22, v2
	v_lshlrev_b32_e32 v9, 2, v2
	v_lshl_add_u64 v[28:29], v[22:23], 2, s[86:87]
	v_lshlrev_b64 v[22:23], 1, v[22:23]
	global_load_dwordx4 v[10:13], v9, s[16:17]
	v_lshl_add_u64 v[30:31], s[42:43], 0, v[22:23]
	v_lshl_add_u64 v[32:33], s[44:45], 0, v[22:23]
	v_lshl_add_u64 v[34:35], s[46:47], 0, v[22:23]
	v_lshl_add_u64 v[36:37], s[14:15], 0, v[22:23]
	global_load_dwordx4 v[22:25], v[28:29], off nt
	global_load_dwordx2 v[38:39], v[30:31], off nt
	global_load_dwordx2 v[40:41], v[32:33], off nt
	global_load_dwordx2 v[42:43], v[34:35], off nt
	global_load_dwordx2 v[44:45], v[36:37], off nt
	v_mad_i64_i32 v[26:27], s[10:11], v26, s2, v[0:1]
	v_lshlrev_b32_e32 v2, 1, v2
	v_lshl_add_u64 v[26:27], v[26:27], 0, v[2:3]
	v_add_u32_e32 v4, s4, v4
	v_cmp_lt_i32_e32 vcc, s3, v4
	s_or_b64 s[8:9], vcc, s[8:9]
	v_add_u32_e32 v7, s0, v7
	s_waitcnt vmcnt(4)
	v_add_f32_e32 v2, v22, v23
	v_add_f32_e32 v2, v2, v24
	s_waitcnt vmcnt(3)
	v_lshlrev_b32_e32 v28, 16, v38
	v_and_b32_e32 v29, 0xffff0000, v38
	s_waitcnt vmcnt(2)
	v_lshlrev_b32_e32 v32, 16, v40
	v_and_b32_e32 v33, 0xffff0000, v40
	v_add_f32_e32 v2, v2, v25
	v_lshlrev_b32_e32 v30, 16, v39
	v_and_b32_e32 v31, 0xffff0000, v39
	v_lshlrev_b32_e32 v34, 16, v41
	v_and_b32_e32 v35, 0xffff0000, v41
	v_pk_mul_f32 v[28:29], v[28:29], v[32:33]
	v_add_f32_dpp v2, v2, v2 quad_perm:[1,0,3,2] row_mask:0xf bank_mask:0xf bound_ctrl:1
	v_pk_mul_f32 v[30:31], v[30:31], v[34:35]
	v_pk_mul_f32 v[10:11], v[10:11], v[28:29]
	v_add_f32_dpp v2, v2, v2 quad_perm:[2,3,0,1] row_mask:0xf bank_mask:0xf bound_ctrl:1
	v_pk_mul_f32 v[12:13], v[12:13], v[30:31]
	v_add_f32_e32 v9, v10, v11
	v_add_f32_dpp v2, v2, v2 row_half_mirror row_mask:0xf bank_mask:0xf bound_ctrl:1
	v_add_f32_e32 v9, v9, v12
	v_add_f32_e32 v9, v13, v9
	v_add_f32_dpp v2, v2, v2 row_ror:8 row_mask:0xf bank_mask:0xf bound_ctrl:1
	v_mul_f32_e32 v2, 0x3c800000, v2
	v_add_f32_dpp v9, v9, v9 quad_perm:[1,0,3,2] row_mask:0xf bank_mask:0xf bound_ctrl:1
	v_pk_add_f32 v[10:11], v[22:23], v[2:3] op_sel_hi:[1,0] neg_lo:[0,1] neg_hi:[0,1]
	v_pk_add_f32 v[12:13], v[24:25], v[2:3] op_sel_hi:[1,0] neg_lo:[0,1] neg_hi:[0,1]
	v_add_f32_dpp v9, v9, v9 quad_perm:[2,3,0,1] row_mask:0xf bank_mask:0xf bound_ctrl:1
	v_pk_mul_f32 v[22:23], v[10:11], v[10:11]
	v_pk_mul_f32 v[24:25], v[12:13], v[12:13]
	v_add_f32_dpp v2, v9, v9 row_half_mirror row_mask:0xf bank_mask:0xf bound_ctrl:1
	v_add_f32_e32 v9, v22, v23
	v_add_f32_e32 v9, v24, v9
	v_add_f32_e32 v9, v25, v9
	s_waitcnt vmcnt(1)
	v_lshlrev_b32_e32 v36, 16, v42
	v_and_b32_e32 v37, 0xffff0000, v42
	v_add_f32_dpp v9, v9, v9 quad_perm:[1,0,3,2] row_mask:0xf bank_mask:0xf bound_ctrl:1
	v_lshlrev_b32_e32 v38, 16, v43
	v_and_b32_e32 v39, 0xffff0000, v43
	v_add_f32_dpp v9, v9, v9 quad_perm:[2,3,0,1] row_mask:0xf bank_mask:0xf bound_ctrl:1
	v_add_f32_dpp v2, v2, v2 row_ror:8 row_mask:0xf bank_mask:0xf bound_ctrl:1
	s_waitcnt vmcnt(0)
	v_lshlrev_b32_e32 v40, 16, v44
	v_add_f32_dpp v9, v9, v9 row_half_mirror row_mask:0xf bank_mask:0xf bound_ctrl:1
	v_and_b32_e32 v41, 0xffff0000, v44
	v_lshlrev_b32_e32 v42, 16, v45
	v_add_f32_dpp v9, v9, v9 row_ror:8 row_mask:0xf bank_mask:0xf bound_ctrl:1
	v_fmamk_f32 v9, v9, 0x3c800000, v8
	v_mul_f32_e32 v22, 0x4b800000, v9
	v_cmp_gt_f32_e32 vcc, s1, v9
	v_and_b32_e32 v43, 0xffff0000, v45
	s_nop 0
	v_cndmask_b32_e32 v9, v9, v22, vcc
	v_rsq_f32_e32 v9, v9
	s_nop 0
	v_mul_f32_e32 v22, 0x45800000, v9
	v_cndmask_b32_e32 v22, v9, v22, vcc
	v_pk_mul_f32 v[10:11], v[10:11], v[22:23] op_sel_hi:[1,0]
	v_pk_mul_f32 v[12:13], v[12:13], v[22:23] op_sel_hi:[1,0]
	v_pk_fma_f32 v[10:11], v[14:15], v[10:11], v[18:19]
	v_pk_fma_f32 v[12:13], v[16:17], v[12:13], v[20:21]
	v_pk_fma_f32 v[10:11], v[2:3], v[36:37], v[10:11] op_sel_hi:[0,1,1]
	v_pk_fma_f32 v[12:13], v[2:3], v[38:39], v[12:13] op_sel_hi:[0,1,1]
	v_pk_mul_f32 v[10:11], v[10:11], v[40:41]
	v_pk_mul_f32 v[12:13], v[12:13], v[42:43]
	v_cvt_pk_bf16_f32 v10, v10, v11
	v_cvt_pk_bf16_f32 v11, v12, v13
	global_store_dwordx2 v[26:27], v[10:11], off offset:1024
	s_andn2_b64 exec, exec, s[8:9]
	s_cbranch_execnz .LBB0_1395
